# scan pass 1: the workgroup barrier at the start of the cumulative-decay stage kept only for the first chunk (later chunks are already ordered by the barrier after the state update)
# baseline (speedup 1.0000x reference)
; #define LAS __attribute__((address_space(3)))
; __device__ __forceinline__ void scan_pass1(const ScanP& sp, int b, int h, int seg, LAS unsigned char* lds) {
;     ...
;         if (ci >= 0) {
;         __syncthreads();
;         {
;             const f32x4 r4 = *(const LAS f32x4*)(stash + tid * 12), v4 = *(const LAS f32x4*)(stash + tid * 12 + 4), kp = *(const LAS f32x4*)(stash + tid * 12 + 8);
;             f32x4 cl = {0.f, 0.f, 0.f, 0.f};
; #pragma unroll 2
;             for (int s4 = 0; s4 < w; ++s4) {
;                 const LAS float* lp_ = lwS + (4 * s4) * 64 + j4;
;                 const f32x4 x0 = *(const LAS f32x4*)lp_, x1 = *(const LAS f32x4*)(lp_ + 64), x2 = *(const LAS f32x4*)(lp_ + 128), x3 = *(const LAS f32x4*)(lp_ + 192);
;                 cl += (x0 + x1) + (x2 + x3);
;             }
; #pragma unroll
;             for (int q = 0; q < 4; ++q) { const int s = 4 * w + q; const f32x4 x = *(const LAS f32x4*)(lwS + s * 64 + j4); if (s <= tt) cl += x; }
;             f32x4 ein, eex, einv;
.LBB0_252:
	v_mov_b32_e32 v108, v160
	s_cmp_gt_i32 s83, -1
	s_cselect_b64 s[70:71], -1, 0
	v_and_b32_e32 v189, 31, v108
	v_ashrrev_i32_e32 v188, 5, v108
	s_cmp_lt_i32 s83, 0
	v_add_u32_e32 v190, 0x1ca00, v184
	s_cbranch_scc1 .LBB0_286
	s_waitcnt lgkmcnt(0)
	s_cmp_lg_u32 s83, 0
	s_cbranch_scc1 .Ls1c_nobar
	s_barrier
.Ls1c_nobar:
	ds_read_b128 v[76:79], v190
	ds_read_b128 v[68:71], v190 offset:16
	ds_read_b128 v[72:75], v190 offset:32
	s_andn2_b64 vcc, exec, s[98:99]
	s_cbranch_vccnz .LBB0_258
	s_andn2_b64 vcc, exec, s[58:59]
	s_cbranch_vccnz .LBB0_259
	v_mov_b32_e32 v80, 0
	s_mov_b32 s0, 0
	v_mov_b32_e32 v0, v183
	v_mov_b32_e32 v81, v80
	v_mov_b32_e32 v82, v80
	v_mov_b32_e32 v83, v80
